# mix2 Q prefetch: loop top waits vmcnt(8) so the eight output stores are not drained there
# baseline (speedup 1.0000x reference)
; __device__ void mix_sweep(const Params& P, LAS unsigned char* lds, int tok0, int pos0, int seqlen, int hd, int dir, bool state_only, bool final_pass,
;                           f32x4 (&Cacc)[9], float& m_state, float& aseg_sum, float lgam) {
;     ...
;     { const int c = dir ? 7 : 0; const int tok = tok0 + c * 128;
; #pragma unroll
;       for (int which = 1; which < 3; ++which) { const int cb = which == 0 ? qcol : (which == 1 ? kcol : vcolg);
; #pragma unroll
;           for (int it = 0; it < 4; ++it) { const int item = tid + 512 * it, r = item >> 4, ch = item & 15; t[which][it] = *(const u32x4*)(proj + (size_t)(tok + r) * NPROJ + cb + 8 * ch); } } }
;     for (int ci = 0; ci < 8; ++ci) {
;         const int c = dir ? 7 - ci : ci; const int tok = tok0 + c * 128;
;         __syncthreads();
;         int tl = tid; asm volatile("" : "+v"(tl));
;         if (!state_only) {
; #pragma unroll
;             for (int it = 0; it < 4; ++it) { const int item = tl + 512 * it, r = item >> 4, ch = item & 15; t[0][it] = *(const u32x4*)(proj + (size_t)(tok + r) * NPROJ + qcol + 8 * ch); } }
.LBB0_96:
	s_and_b64 s[14:15], s[8:9], exec
	v_and_b32_e32 v0, 0x78, v0
	s_cselect_b32 s14, 0, 0x380
	v_lshlrev_b32_e32 v0, 1, v0
	s_or_b32 s14, s14, s79
	s_waitcnt lgkmcnt(2)
	v_lshl_add_u64 v[2:3], s[22:23], 0, v[0:1]
	v_ashrrev_i32_e32 v0, 4, v161
	v_add_u32_e32 v40, s14, v0
	v_add_u32_e32 v0, 0x200, v161
	v_ashrrev_i32_e32 v0, 4, v0
	v_add_u32_e32 v42, s14, v0
	v_add_u32_e32 v0, 0x400, v161
	v_ashrrev_i32_e32 v0, 4, v0
	v_add_u32_e32 v50, s14, v0
	v_add_u32_e32 v0, 0x600, v161
	v_ashrrev_i32_e32 v0, 4, v0
	v_add_u32_e32 v52, s14, v0
	v_ashrrev_i32_e32 v41, 31, v40
	s_lshl_b32 s38, s80, 1
	v_ashrrev_i32_e32 v43, 31, v42
	v_ashrrev_i32_e32 v51, 31, v50
	v_ashrrev_i32_e32 v53, 31, v52
	s_lshl_b32 s14, s81, 1
	s_mov_b32 s15, s39
	v_lshlrev_b64 v[56:57], 13, v[40:41]
	v_lshl_add_u64 v[48:49], v[2:3], 0, s[38:39]
	v_lshlrev_b64 v[58:59], 13, v[42:43]
	v_lshlrev_b64 v[64:65], 13, v[50:51]
	v_lshlrev_b64 v[66:67], 13, v[52:53]
	v_lshl_add_u64 v[2:3], v[2:3], 0, s[14:15]
	v_lshl_add_u64 v[40:41], v[48:49], 0, v[56:57]
	v_lshl_add_u64 v[44:45], v[48:49], 0, v[58:59]
	v_lshl_add_u64 v[50:51], v[48:49], 0, v[64:65]
	v_lshl_add_u64 v[52:53], v[48:49], 0, v[66:67]
	v_lshl_add_u64 v[56:57], v[2:3], 0, v[56:57]
	v_lshl_add_u64 v[60:61], v[2:3], 0, v[58:59]
	v_lshl_add_u64 v[64:65], v[2:3], 0, v[64:65]
	global_load_dwordx4 v[40:43], v[40:41], off
	s_nop 0
	global_load_dwordx4 v[44:47], v[44:45], off
	s_nop 0
	global_load_dwordx4 v[48:51], v[50:51], off
	s_nop 0
	global_load_dwordx4 v[52:55], v[52:53], off
	s_nop 0
	global_load_dwordx4 v[56:59], v[56:57], off
	s_nop 0
	global_load_dwordx4 v[60:63], v[60:61], off
	v_lshl_add_u64 v[2:3], v[2:3], 0, v[66:67]
	global_load_dwordx4 v[64:67], v[64:65], off
	s_nop 0
	global_load_dwordx4 v[68:71], v[2:3], off
	v_lshlrev_b32_e32 v79, 2, v161
	s_add_i32 s15, 0, 0x22000
	v_add_u32_e32 v182, s15, v79
	s_add_i32 s15, 0, 0x22200
	v_lshlrev_b32_e32 v0, 4, v73
	v_add_u32_e32 v183, s15, v79
	v_add_u32_e32 v190, s15, v0
	v_readlane_b32 s15, v253, 49
	s_add_i32 s19, 0, 0x22400
	v_add_u32_e32 v184, s19, v79
	v_add_u32_e32 v194, s15, v75
	s_add_i32 s15, 0, 0x1a000
	v_add_u32_e32 v195, s15, v75
	v_readlane_b32 s15, v253, 50
	s_add_i32 s19, 0, 0x22600
	s_add_i32 s46, 0, 0x22800
	v_add_u32_e32 v196, s15, v75
	s_add_i32 s15, 0, 0x1c000
	v_add_u32_e32 v197, s15, v75
	v_readlane_b32 s15, v253, 51
	v_lshlrev_b32_e32 v189, 2, v73
	v_mov_b32_e32 v73, v1
	v_add_u32_e32 v198, s15, v75
	s_add_i32 s15, 0, 0x1e000
	v_add_u32_e32 v199, s15, v75
	v_readlane_b32 s15, v253, 52
	s_add_i32 s85, 0, 0x10000
	s_mov_b32 s7, 0
	v_add_u32_e32 v200, s15, v75
	v_readlane_b32 s15, v253, 53
	s_mov_b32 s83, 1
	v_add_u32_e32 v185, s19, v79
	v_add_u32_e32 v247, s15, v75
	s_add_i32 s15, 0, 0x12000
	v_add_u32_e32 v248, s15, v75
	v_readlane_b32 s15, v253, 54
	v_add_u32_e32 v187, s46, v79
	v_cmp_eq_u32_e64 s[46:47], 0, v161
	v_add_u32_e32 v249, s15, v75
	s_add_i32 s15, 0, 0x14000
	v_add_u32_e32 v250, s15, v75
	v_readlane_b32 s15, v253, 55
	v_lshl_or_b32 v219, s16, 4, v169
	s_add_i32 s84, s17, 0
	v_add_u32_e32 v251, s15, v75
	s_add_i32 s15, 0, 0x16000
	v_add_u32_e32 v252, s15, v75
	v_readlane_b32 s15, v253, 56
	v_add_u32_e32 v191, 0, v78
	v_lshl_add_u32 v192, v72, 2, s19
	v_lshl_add_u64 v[2:3], s[2:3], 0, v[72:73]
	v_lshl_add_u64 v[152:153], s[4:5], 0, v[72:73]
	v_lshl_add_u64 v[154:155], s[94:95], 0, v[0:1]
	v_add_u32_e32 v193, s18, v75
	v_or_b32_e32 v201, 2, v189
	v_or_b32_e32 v202, 3, v189
	v_or_b32_e32 v204, 16, v189
	v_or_b32_e32 v205, 17, v189
	v_or_b32_e32 v206, 18, v189
	v_or_b32_e32 v207, 19, v189
	v_or_b32_e32 v222, 32, v189
	v_or_b32_e32 v223, 33, v189
	v_or_b32_e32 v224, 34, v189
	v_or_b32_e32 v225, 35, v189
	v_or_b32_e32 v226, 48, v189
	v_or_b32_e32 v227, 49, v189
	v_or_b32_e32 v228, 50, v189
	v_or_b32_e32 v229, 51, v189
	v_or_b32_e32 v230, 64, v189
	v_or_b32_e32 v231, 0x41, v189
	v_or_b32_e32 v232, 0x42, v189
	v_or_b32_e32 v233, 0x43, v189
	v_or_b32_e32 v234, 0x50, v189
	v_or_b32_e32 v235, 0x51, v189
	v_or_b32_e32 v236, 0x52, v189
	v_or_b32_e32 v237, 0x53, v189
	v_or_b32_e32 v238, 0x60, v189
	v_or_b32_e32 v239, 0x61, v189
	v_or_b32_e32 v240, 0x62, v189
	v_or_b32_e32 v241, 0x63, v189
	v_or_b32_e32 v242, 0x70, v189
	v_or_b32_e32 v243, 0x71, v189
	v_or_b32_e32 v244, 0x72, v189
	v_or_b32_e32 v245, 0x73, v189
	v_add_u32_e32 v246, s85, v75
	v_add_u32_e32 v211, s15, v75
	v_add_u32_e32 v164, 0, v79
	s_mov_b32 s86, 6
	s_movk_i32 s87, 0xd000
	v_add_u32_e32 v165, 0, v76
	v_add_u32_e32 v166, 0, v77
	v_add_u32_e32 v167, 0, v74
	v_readlane_b32 s88, v253, 57
	v_lshrrev_b32_e32 v80, 6, v161
	v_lshlrev_b32_e32 v80, 6, v80
	v_mov_b32_e32 v81, 0
	v_lshl_add_u64 v[82:83], v[154:155], 0, v[80:81]
	global_load_dwordx4 v[84:87], v[82:83], off
	v_bfe_u32 v81, v161, 4, 2
	v_lshl_add_u32 v80, v81, 4, v80
	v_add_u32_e32 v80, 0x25a80, v80
	s_waitcnt vmcnt(0)
	ds_write_b128 v80, v[84:87]
	s_mov_b32 s32, s7
	s_xor_b32 s89, s32, 0x380
	s_cmp_lg_u64 s[8:9], 0
	s_cselect_b32 s32, s32, s89
	s_add_i32 s32, s32, s79
	v_ashrrev_i32_e32 v194, 4, v161
	v_lshlrev_b32_e32 v198, 4, v161
	v_add_u32_e32 v194, s32, v194
	v_and_b32_e32 v198, 0xf0, v198
	v_ashrrev_i32_e32 v195, 31, v194
	v_mov_b32_e32 v199, 0
	v_lshlrev_b64 v[194:195], 13, v[194:195]
	v_lshl_add_u64 v[198:199], s[36:37], 0, v[198:199]
	v_mov_b32_e32 v242, 0x40000
	v_mov_b32_e32 v243, 0
	v_lshl_add_u64 v[194:195], v[198:199], 0, v[194:195]
	v_lshl_add_u64 v[198:199], v[194:195], 0, v[242:243]
	v_lshl_add_u64 v[244:245], v[198:199], 0, v[242:243]
	v_lshl_add_u64 v[154:155], v[244:245], 0, v[242:243]
	s_nop 0
	global_load_dwordx4 v[194:197], v[194:195], off
	s_nop 0
	global_load_dwordx4 v[198:201], v[198:199], off
	s_nop 0
	global_load_dwordx4 v[242:245], v[244:245], off
	s_nop 0
	global_load_dword v202, v[154:155], off offset:8
	s_nop 0
	global_load_dword v186, v[154:155], off offset:12
	s_nop 0
	global_load_dwordx2 v[154:155], v[154:155], off
	s_waitcnt vmcnt(0)
	s_branch .LBB0_98
.Lqpf_stub:
	s_cmpk_eq_i32 s87, 0xfa00
	s_cbranch_scc1 .Lqpf_skip_s
	s_add_i32 s32, s7, 0x80
	s_xor_b32 s89, s32, 0x380
	s_cmp_lg_u64 s[8:9], 0
	s_cselect_b32 s32, s32, s89
	s_add_i32 s32, s32, s79
	v_ashrrev_i32_e32 v194, 4, v161
	v_lshlrev_b32_e32 v198, 4, v161
	v_add_u32_e32 v194, s32, v194
	v_and_b32_e32 v198, 0xf0, v198
	v_ashrrev_i32_e32 v195, 31, v194
	v_mov_b32_e32 v199, 0
	v_lshlrev_b64 v[194:195], 13, v[194:195]
	v_lshl_add_u64 v[198:199], s[36:37], 0, v[198:199]
	v_mov_b32_e32 v242, 0x40000
	v_mov_b32_e32 v243, 0
	v_lshl_add_u64 v[194:195], v[198:199], 0, v[194:195]
	v_lshl_add_u64 v[198:199], v[194:195], 0, v[242:243]
	v_lshl_add_u64 v[244:245], v[198:199], 0, v[242:243]
	v_lshl_add_u64 v[154:155], v[244:245], 0, v[242:243]
	s_nop 0
	global_load_dwordx4 v[194:197], v[194:195], off
	s_nop 0
	global_load_dwordx4 v[198:201], v[198:199], off
	s_nop 0
	global_load_dwordx4 v[242:245], v[244:245], off
	s_nop 0
	global_load_dword v202, v[154:155], off offset:8
	s_nop 0
	global_load_dword v186, v[154:155], off offset:12
	s_nop 0
	global_load_dwordx2 v[154:155], v[154:155], off
	s_waitcnt vmcnt(0)

; #define LAS __attribute__((address_space(3)))
; __device__ void mix_sweep(const Params& P, LAS unsigned char* lds, int tok0, int pos0, int seqlen, int hd, int dir, bool state_only, bool final_pass,
;                           f32x4 (&Cacc)[9], float& m_state, float& aseg_sum, float lgam) {
;     ...
;         const int c = dir ? 7 - ci : ci; const int tok = tok0 + c * 128;
;         __syncthreads();
;         int tl = tid; asm volatile("" : "+v"(tl));
;         if (!state_only) {
; #pragma unroll
;             for (int it = 0; it < 4; ++it) { const int item = tl + 512 * it, r = item >> 4, ch = item & 15; t[0][it] = *(const u32x4*)(proj + (size_t)(tok + r) * NPROJ + qcol + 8 * ch); } }
; #pragma unroll
;     ...
; #pragma unroll
;             for (int it = 0; it < 4; ++it) { const int item = tl + 512 * it, r = item >> 4, ch = item & 15; *(LAS u32x4*)(img + offb(r, ch)) = t[which][it]; } }
;         if (ci < 7) { const int cn = dir ? 6 - ci : ci + 1; const int tokn = tok0 + cn * 128;
; #pragma unroll
;             for (int which = 1; which < 3; ++which) { const int cb = which == 1 ? kcol : vcolg;
; #pragma unroll
;                 for (int it = 0; it < 4; ++it) { const int item = tl + 512 * it, r = item >> 4, ch = item & 15; t[which][it] = *(const u32x4*)(proj + (size_t)(tokn + r) * NPROJ + cb + 8 * ch); } } }
.LBB0_98:
	s_xor_b32 s15, s7, 0x380
	s_and_b64 s[16:17], s[8:9], exec
	s_cselect_b32 s89, s7, s15
	v_mov_b32_e32 v92, v161
	s_add_i32 s89, s89, s79
	s_waitcnt lgkmcnt(0)
	s_barrier
	s_cmpk_eq_i32 s87, 0xfa00
	v_lshlrev_b32_e32 v0, 3, v92
	v_ashrrev_i32_e32 v72, 4, v92
	v_and_b32_e32 v0, 0x78, v0
	v_lshlrev_b32_e32 v0, 1, v0
	v_add_u32_e32 v73, 0x200, v92
	v_ashrrev_i32_e32 v73, 4, v73
	v_add_u32_e32 v74, 0x400, v92
	v_ashrrev_i32_e32 v74, 4, v74
	v_add_u32_e32 v75, 0x600, v92
	v_ashrrev_i32_e32 v75, 4, v75
	v_lshlrev_b32_e32 v94, 2, v72
	v_and_b32_e32 v92, 15, v92
	v_and_b32_e32 v94, 12, v94
	v_bfe_u32 v95, v72, 2, 2
	v_bitop3_b32 v94, v94, v92, v95 bitop3:0x36
	v_lshlrev_b32_e32 v96, 2, v73
	v_lshlrev_b32_e32 v93, 8, v72
	v_lshlrev_b32_e32 v94, 4, v94
	v_and_b32_e32 v96, 12, v96
	v_bfe_u32 v97, v73, 2, 2
	v_add3_u32 v95, s85, v94, v93
	v_bitop3_b32 v96, v96, v92, v97 bitop3:0x36
	v_lshlrev_b32_e32 v98, 2, v74
	s_waitcnt vmcnt(8)
	ds_write_b128 v95, v[56:59]
	v_lshlrev_b32_e32 v95, 8, v73
	v_lshlrev_b32_e32 v96, 4, v96
	v_and_b32_e32 v98, 12, v98
	v_bfe_u32 v99, v74, 2, 2
	v_add3_u32 v97, s85, v96, v95
	v_bitop3_b32 v98, v98, v92, v99 bitop3:0x36
	v_lshlrev_b32_e32 v100, 2, v75
	ds_write_b128 v97, v[60:63]
	v_lshlrev_b32_e32 v97, 8, v74
	v_lshlrev_b32_e32 v98, 4, v98
	v_and_b32_e32 v100, 12, v100
	v_bfe_u32 v101, v75, 2, 2
	v_add3_u32 v99, s85, v98, v97
	v_bitop3_b32 v92, v100, v92, v101 bitop3:0x36
	ds_write_b128 v99, v[64:67]
	v_lshlrev_b32_e32 v99, 8, v75
	v_lshlrev_b32_e32 v92, 4, v92
	v_add3_u32 v100, s85, v92, v99
	v_add3_u32 v93, 0, v94, v93
	v_add3_u32 v94, 0, v96, v95
	v_add3_u32 v95, 0, v98, v97
	v_add3_u32 v92, 0, v92, v99
	ds_write_b128 v100, v[68:71]
	ds_write_b128 v93, v[40:43] offset:32768
	ds_write_b128 v94, v[44:47] offset:32768
	ds_write_b128 v95, v[48:51] offset:32768
	ds_write_b128 v92, v[52:55] offset:32768
	ds_write_b128 v93, v[194:197]
	ds_write_b128 v94, v[198:201]
	ds_write_b128 v95, v[242:245]
	ds_write_b64 v92, v[154:155]
	ds_write_b32 v92, v202 offset:8
	ds_write_b32 v92, v186 offset:12
	s_cbranch_scc1 .LBB0_100
	s_and_b64 s[16:17], s[8:9], exec
	s_cselect_b32 s15, s83, s86
	s_lshl_b32 s15, s15, 7
	s_add_i32 s15, s15, s79
	v_add_u32_e32 v40, s15, v72
	v_add_u32_e32 v42, s15, v73
	v_add_u32_e32 v50, s15, v74
	v_add_u32_e32 v52, s15, v75
	v_lshl_add_u64 v[56:57], s[22:23], 0, v[0:1]
	v_ashrrev_i32_e32 v41, 31, v40
	v_ashrrev_i32_e32 v43, 31, v42
	v_ashrrev_i32_e32 v51, 31, v50
	v_ashrrev_i32_e32 v53, 31, v52
	s_mov_b32 s15, s39
	v_lshlrev_b64 v[58:59], 13, v[40:41]
	v_lshl_add_u64 v[48:49], v[56:57], 0, s[38:39]
	v_lshlrev_b64 v[60:61], 13, v[42:43]
	v_lshlrev_b64 v[64:65], 13, v[50:51]
	v_lshlrev_b64 v[66:67], 13, v[52:53]
	v_lshl_add_u64 v[68:69], v[56:57], 0, s[14:15]
	v_lshl_add_u64 v[40:41], v[48:49], 0, v[58:59]
	v_lshl_add_u64 v[44:45], v[48:49], 0, v[60:61]
	v_lshl_add_u64 v[50:51], v[48:49], 0, v[64:65]
	v_lshl_add_u64 v[52:53], v[48:49], 0, v[66:67]
	v_lshl_add_u64 v[56:57], v[68:69], 0, v[58:59]
	v_lshl_add_u64 v[60:61], v[68:69], 0, v[60:61]
	v_lshl_add_u64 v[64:65], v[68:69], 0, v[64:65]
	v_lshl_add_u64 v[68:69], v[68:69], 0, v[66:67]
	global_load_dwordx4 v[40:43], v[40:41], off
	s_nop 0
	global_load_dwordx4 v[44:47], v[44:45], off
	s_nop 0
	global_load_dwordx4 v[48:51], v[50:51], off
	s_nop 0
	global_load_dwordx4 v[52:55], v[52:53], off
	s_nop 0
	global_load_dwordx4 v[56:59], v[56:57], off
	s_nop 0
	global_load_dwordx4 v[60:63], v[60:61], off
	s_nop 0
	global_load_dwordx4 v[64:67], v[64:65], off
	s_nop 0
	global_load_dwordx4 v[68:71], v[68:69], off
